# rmsnorm-residual passes and X-convert prologue: wave-sum ds_bpermute butterflies replaced by DPP quad_perm/row_half_mirror/row_mirror moves and permlane16/32 swaps (no LDS round trips); bit-identical
# speedup vs baseline: 1.0054x; 1.0034x over previous
; __device__ __forceinline__ unsigned pk2(float lo, float hi) { return f2bf(lo) | (f2bf(hi) << 16); }
; __device__ __forceinline__ float wave_sum(float v) {
; #pragma unroll
;     for (int o = 1; o < 64; o <<= 1) v += __shfl_xor(v, o);
;     return v;
; }
; __device__ __forceinline__ void p0_prologue(const Args& a, LAS unsigned char* lds, int gw, int NGW, int wave, int lane) {
;     ...
;             if (r < ROWS_P) { const int s = r / L_P, pos = r - s * L_P; src = (pos < 16) ? a.in[2] + pos * 1024 : a.in[0] + ((size_t)s * 2048 + (pos - 16)) * 1024; }
;             else { const int q = r - ROWS_P, s = q / L_S, pos = q - s * L_S; src = (pos < 16) ? a.in[2] + pos * 1024 : a.in[1] + ((size_t)s * 16384 + (pos - 16)) * 1024; }
;             const f32x4* xr = (const f32x4*)src + lane;
;             f32x4 v[4]; float s2 = 0.f;
; #pragma unroll
;             for (int j = 0; j < 4; ++j) { v[j] = xr[64 * j]; s2 += (v[j].x * v[j].x + v[j].y * v[j].y) + (v[j].z * v[j].z + v[j].w * v[j].w); }
;             s2 = wave_sum(s2);
; #pragma unroll
;             for (int j = 0; j < 4; ++j) o8[64 * j] = (v2u){pk2(v[j].x, v[j].y), pk2(v[j].z, v[j].w)};
;             if (lane == 0) ssqX[r] = s2;
.LBB0_159:
	v_lshl_add_u64 v[30:31], v[2:3], 4, s[16:17]
	s_waitcnt lgkmcnt(0)
	global_load_dwordx4 v[14:17], v[30:31], off
	global_load_dwordx4 v[18:21], v[30:31], off offset:1024
	global_load_dwordx4 v[22:25], v[30:31], off offset:2048
	global_load_dwordx4 v[26:29], v[30:31], off offset:3072
	v_cmp_lt_i32_e32 vcc, v8, v7
	s_mov_b64 s[18:19], 0
	s_mov_b64 s[16:17], 0
	v_cndmask_b32_e32 v30, v6, v8, vcc
	v_lshlrev_b32_e32 v30, 2, v30
	v_cmp_lt_i32_e32 vcc, v9, v7
	s_waitcnt vmcnt(3)
	v_mul_f32_e32 v36, v15, v15
	v_mul_f32_e32 v37, v17, v17
	s_waitcnt vmcnt(2)
	v_mul_f32_e32 v38, v19, v19
	v_mul_f32_e32 v39, v21, v21
	s_waitcnt vmcnt(1)
	v_mul_f32_e32 v40, v23, v23
	v_mul_f32_e32 v41, v25, v25
	v_fmac_f32_e32 v36, v14, v14
	v_fmac_f32_e32 v37, v16, v16
	v_fmac_f32_e32 v38, v18, v18
	v_fmac_f32_e32 v39, v20, v20
	s_waitcnt vmcnt(0)
	v_mul_f32_e32 v42, v27, v27
	v_mul_f32_e32 v43, v29, v29
	v_fmac_f32_e32 v40, v22, v22
	v_fmac_f32_e32 v41, v24, v24
	v_add_f32_e32 v36, v36, v37
	v_add_f32_e32 v37, v38, v39
	v_fmac_f32_e32 v42, v26, v26
	v_fmac_f32_e32 v43, v28, v28
	v_add_f32_e32 v38, v40, v41
	v_add_f32_e32 v36, v36, v37
	v_add_f32_e32 v39, v42, v43
	v_add_f32_e32 v36, v36, v38
	v_add_f32_e32 v36, v36, v39
	s_nop 1
	v_mov_b32_dpp v30, v36 quad_perm:[1,0,3,2] row_mask:0xf bank_mask:0xf
	v_cndmask_b32_e32 v31, v6, v9, vcc
	v_lshlrev_b32_e32 v31, 2, v31
	v_cmp_lt_i32_e32 vcc, v10, v7
	v_bfe_u32 v44, v14, 16, 1
	s_waitcnt lgkmcnt(0)
	v_add_f32_e32 v30, v36, v30
	s_nop 1
	v_mov_b32_dpp v31, v30 quad_perm:[2,3,0,1] row_mask:0xf bank_mask:0xf
	v_cndmask_b32_e32 v32, v6, v10, vcc
	v_lshlrev_b32_e32 v32, 2, v32
	v_cmp_lt_i32_e32 vcc, v11, v7
	v_bfe_u32 v46, v16, 16, 1
	s_waitcnt lgkmcnt(0)
	v_add_f32_e32 v30, v30, v31
	s_nop 1
	v_mov_b32_dpp v31, v30 row_half_mirror row_mask:0xf bank_mask:0xf
	v_cndmask_b32_e32 v33, v6, v11, vcc
	v_lshlrev_b32_e32 v33, 2, v33
	v_bfe_u32 v50, v20, 16, 1
	v_cmp_lt_i32_e32 vcc, v12, v7
	s_waitcnt lgkmcnt(0)
	v_add_f32_e32 v30, v30, v31
	s_nop 1
	v_mov_b32_dpp v31, v30 row_mirror row_mask:0xf bank_mask:0xf
	v_bfe_u32 v45, v15, 16, 1
	v_bfe_u32 v47, v17, 16, 1
	v_bfe_u32 v48, v18, 16, 1
	v_bfe_u32 v51, v21, 16, 1
	v_bfe_u32 v52, v22, 16, 1
	v_add3_u32 v14, v14, v44, s25
	v_add3_u32 v16, v16, v46, s25
	v_add3_u32 v20, v20, v50, s25
	v_cndmask_b32_e32 v34, v6, v12, vcc
	v_bfe_u32 v49, v19, 16, 1
	v_bfe_u32 v53, v23, 16, 1
	v_add3_u32 v15, v15, v45, s25
	v_add3_u32 v17, v17, v47, s25
	v_add3_u32 v18, v18, v48, s25
	v_add3_u32 v21, v21, v51, s25
	v_add3_u32 v22, v22, v52, s25
	v_lshrrev_b32_e32 v14, 16, v14
	v_lshrrev_b32_e32 v16, 16, v16
	v_lshrrev_b32_e32 v20, 16, v20
	v_lshlrev_b32_e32 v34, 2, v34
	v_add3_u32 v19, v19, v49, s25
	v_add3_u32 v23, v23, v53, s25
	v_lshrrev_b32_e32 v18, 16, v18
	v_lshrrev_b32_e32 v22, 16, v22
	v_and_or_b32 v14, v15, s31, v14
	v_and_or_b32 v15, v17, s31, v16
	v_and_or_b32 v17, v21, s31, v20
	s_waitcnt lgkmcnt(0)
	v_add_f32_e32 v21, v30, v31
	v_and_or_b32 v16, v19, s31, v18
	v_and_or_b32 v18, v23, s31, v22
	v_mov_b32_e32 v22, v21
	s_nop 1
	v_permlane16_swap_b32_e32 v22, v21
	v_bfe_u32 v54, v24, 16, 1
	v_cmp_lt_i32_e32 vcc, v13, v7
	v_bfe_u32 v55, v25, 16, 1
	v_add3_u32 v24, v24, v54, s25
	v_cndmask_b32_e32 v35, v6, v13, vcc
	v_add3_u32 v25, v25, v55, s25
	v_lshrrev_b32_e32 v24, 16, v24
	v_lshlrev_b32_e32 v35, 2, v35
	v_and_or_b32 v19, v25, s31, v24
	global_store_dwordx2 v[4:5], v[14:15], off offset:-1024
	global_store_dwordx2 v[4:5], v[16:17], off offset:-512
	global_store_dwordx2 v[4:5], v[18:19], off
	s_waitcnt lgkmcnt(0)
	v_add_f32_e32 v15, v21, v22
	v_mov_b32_e32 v16, v15
	s_nop 1
	v_permlane32_swap_b32_e32 v16, v15
	v_bfe_u32 v56, v26, 16, 1
	v_bfe_u32 v58, v28, 16, 1
	v_bfe_u32 v57, v27, 16, 1
	v_bfe_u32 v59, v29, 16, 1
	v_add3_u32 v26, v26, v56, s25
	v_add3_u32 v28, v28, v58, s25
	v_add3_u32 v27, v27, v57, s25
	v_lshrrev_b32_e32 v26, 16, v26
	v_lshrrev_b32_e32 v28, 16, v28
	v_add3_u32 v14, v29, v59, s25
	v_and_or_b32 v20, v27, s31, v26
	v_and_or_b32 v21, v14, s31, v28
	global_store_dwordx2 v[4:5], v[20:21], off offset:512
	s_and_saveexec_b64 s[26:27], s[2:3]
	s_xor_b64 s[26:27], exec, s[26:27]
	s_cbranch_execz .LBB0_161
	s_mov_b64 s[16:17], exec
	s_waitcnt lgkmcnt(0)
	v_add_f32_e32 v14, v15, v16

; __device__ __forceinline__ float half_sum32(float v) {
; #pragma unroll
;     for (int o = 1; o < 32; o <<= 1) v += __shfl_xor(v, o);
;     return v;
; }
; __device__ __forceinline__ void nr_pass(bf16* X, const bf16* Y, const float* SSQ, float* ssqX, const float* g, float* out  , int gw, int NGW, int lane) {
;     ...
;     for (int r = gw; r < M_REAL; r += NGW) {
;         const float part = SSQ[(size_t)r * 32 + (lane & 31)];
;         const float s = rsqrtf(half_sum32(part) * (1.0f / 1024.0f) + EPS);
;         v2u* x8 = (v2u*)(X + (size_t)r * 1024) + lane; const v2u* y8 = (const v2u*)(Y + (size_t)r * 1024) + lane;
;         f32x4 v[4]; float s2 = 0.f;
; #pragma unroll
;         for (int j = 0; j < 4; ++j) { const v2u xv = x8[64 * j], yv = __builtin_nontemporal_load(&y8[64 * j]);
;             v[j].x = bflo(xv.x) + bflo(yv.x) * s * gv[j].x; v[j].y = bfhi(xv.x) + bfhi(yv.x) * s * gv[j].y;
;             v[j].z = bflo(xv.y) + bflo(yv.y) * s * gv[j].z; v[j].w = bfhi(xv.y) + bfhi(yv.y) * s * gv[j].w;
;             s2 += (v[j].x * v[j].x + v[j].y * v[j].y) + (v[j].z * v[j].z + v[j].w * v[j].w); }
.LBB0_744:
	global_load_dword v31, v[18:19], off
	v_lshl_add_u64 v[14:15], s[14:15], 0, v[20:21]
	v_lshl_add_u64 v[34:35], s[2:3], 0, v[20:21]
	s_waitcnt lgkmcnt(0)
	global_load_dwordx2 v[32:33], v[14:15], off offset:-1024
	global_load_dwordx2 v[36:37], v[34:35], off nt
	global_load_dwordx2 v[38:39], v[14:15], off offset:-512
	global_load_dwordx2 v[40:41], v[34:35], off offset:512 nt
	global_load_dwordx2 v[42:43], v[14:15], off
	global_load_dwordx2 v[44:45], v[34:35], off offset:1024 nt
	global_load_dwordx2 v[46:47], v[14:15], off offset:512
	global_load_dwordx2 v[48:49], v[34:35], off offset:1536 nt
	s_waitcnt vmcnt(6)
	v_lshlrev_b32_e32 v51, 16, v37
	v_lshlrev_b32_e32 v50, 16, v36
	s_nop 1
	v_mov_b32_dpp v56, v31 quad_perm:[1,0,3,2] row_mask:0xf bank_mask:0xf
	v_and_b32_e32 v37, 0xffff0000, v37
	v_and_b32_e32 v36, 0xffff0000, v36
	s_waitcnt vmcnt(4)
	v_lshlrev_b32_e32 v55, 16, v41
	v_lshlrev_b32_e32 v54, 16, v40
	s_waitcnt lgkmcnt(0)
	v_add_f32_e32 v31, v31, v56
	s_nop 1
	v_mov_b32_dpp v56, v31 quad_perm:[2,3,0,1] row_mask:0xf bank_mask:0xf
	v_and_b32_e32 v41, 0xffff0000, v41
	v_and_b32_e32 v40, 0xffff0000, v40
	v_lshlrev_b32_e32 v35, 16, v33
	v_lshlrev_b32_e32 v34, 16, v32
	s_waitcnt lgkmcnt(0)
	v_add_f32_e32 v31, v31, v56
	s_nop 1
	v_mov_b32_dpp v60, v31 row_half_mirror row_mask:0xf bank_mask:0xf
	v_and_b32_e32 v33, 0xffff0000, v33
	v_and_b32_e32 v32, 0xffff0000, v32
	v_lshlrev_b32_e32 v53, 16, v39
	v_lshlrev_b32_e32 v52, 16, v38
	s_waitcnt lgkmcnt(0)
	v_add_f32_e32 v31, v31, v60
	s_nop 1
	v_mov_b32_dpp v60, v31 row_mirror row_mask:0xf bank_mask:0xf
	v_and_b32_e32 v39, 0xffff0000, v39
	v_and_b32_e32 v38, 0xffff0000, v38
	s_waitcnt vmcnt(2)
	v_lshlrev_b32_e32 v59, 16, v45
	v_lshlrev_b32_e32 v58, 16, v44
	s_waitcnt lgkmcnt(0)
	v_add_f32_e32 v31, v31, v60
	v_mov_b32_e32 v64, v31
	s_nop 1
	v_permlane16_swap_b32_e32 v64, v31
	v_and_b32_e32 v45, 0xffff0000, v45
	v_and_b32_e32 v44, 0xffff0000, v44
	s_waitcnt vmcnt(0)
	v_lshlrev_b32_e32 v63, 16, v49
	v_lshlrev_b32_e32 v62, 16, v48
	s_waitcnt lgkmcnt(0)
	v_add_f32_e32 v31, v31, v64
	v_fmamk_f32 v31, v31, 0x3a800000, v24
	v_mul_f32_e32 v64, 0x4b800000, v31
	v_cmp_gt_f32_e64 s[0:1], s19, v31
	v_and_b32_e32 v49, 0xffff0000, v49
	v_and_b32_e32 v48, 0xffff0000, v48
	v_cndmask_b32_e64 v31, v31, v64, s[0:1]
	v_rsq_f32_e32 v31, v31
	v_lshlrev_b32_e32 v57, 16, v43
	v_lshlrev_b32_e32 v56, 16, v42
	v_and_b32_e32 v43, 0xffff0000, v43
	v_mul_f32_e32 v64, 0x45800000, v31
	v_cndmask_b32_e64 v64, v31, v64, s[0:1]
	v_pk_mul_f32 v[36:37], v[64:65], v[36:37] op_sel_hi:[0,1]
	v_pk_mul_f32 v[40:41], v[64:65], v[40:41] op_sel_hi:[0,1]
	v_and_b32_e32 v42, 0xffff0000, v42
	v_lshlrev_b32_e32 v61, 16, v47
	v_lshlrev_b32_e32 v60, 16, v46
	v_and_b32_e32 v47, 0xffff0000, v47
	v_and_b32_e32 v46, 0xffff0000, v46
	v_pk_mul_f32 v[50:51], v[64:65], v[50:51] op_sel_hi:[0,1]
	v_pk_mul_f32 v[54:55], v[64:65], v[54:55] op_sel_hi:[0,1]
	v_pk_mul_f32 v[58:59], v[64:65], v[58:59] op_sel_hi:[0,1]
	v_pk_mul_f32 v[44:45], v[64:65], v[44:45] op_sel_hi:[0,1]
	v_pk_mul_f32 v[48:49], v[64:65], v[48:49] op_sel_hi:[0,1]
	v_pk_fma_f32 v[32:33], v[22:23], v[36:37], v[32:33]
	v_pk_fma_f32 v[38:39], v[2:3], v[40:41], v[38:39]
	v_pk_fma_f32 v[34:35], v[0:1], v[50:51], v[34:35]
	v_pk_fma_f32 v[36:37], v[4:5], v[54:55], v[52:53]
	v_pk_fma_f32 v[40:41], v[8:9], v[58:59], v[56:57]
	v_pk_fma_f32 v[42:43], v[6:7], v[44:45], v[42:43]
	v_pk_fma_f32 v[46:47], v[10:11], v[48:49], v[46:47]
	v_pk_mul_f32 v[48:49], v[32:33], v[32:33]
	v_and_b32_sdwa v57, v33, v16 dst_sel:DWORD dst_unused:UNUSED_PAD src0_sel:WORD_1 src1_sel:DWORD
	v_and_b32_sdwa v58, v32, v16 dst_sel:DWORD dst_unused:UNUSED_PAD src0_sel:WORD_1 src1_sel:DWORD
	v_pk_mul_f32 v[50:51], v[38:39], v[38:39]
	v_pk_mul_f32 v[62:63], v[64:65], v[62:63] op_sel_hi:[0,1]
	v_and_b32_sdwa v31, v35, v16 dst_sel:DWORD dst_unused:UNUSED_PAD src0_sel:WORD_1 src1_sel:DWORD
	v_and_b32_sdwa v56, v34, v16 dst_sel:DWORD dst_unused:UNUSED_PAD src0_sel:WORD_1 src1_sel:DWORD
	v_pk_mul_f32 v[52:53], v[42:43], v[42:43]
	v_pk_fma_f32 v[48:49], v[34:35], v[34:35], v[48:49]
	v_add3_u32 v57, v33, v57, s20
	v_add3_u32 v58, v32, v58, s20
	v_pk_fma_f32 v[32:33], v[36:37], v[36:37], v[50:51]
	v_pk_fma_f32 v[44:45], v[12:13], v[62:63], v[60:61]
	v_and_b32_sdwa v59, v37, v16 dst_sel:DWORD dst_unused:UNUSED_PAD src0_sel:WORD_1 src1_sel:DWORD
	v_and_b32_sdwa v60, v36, v16 dst_sel:DWORD dst_unused:UNUSED_PAD src0_sel:WORD_1 src1_sel:DWORD
	v_pk_mul_f32 v[54:55], v[46:47], v[46:47]
	v_add3_u32 v56, v34, v56, s20
	v_add3_u32 v31, v35, v31, s20
	v_pk_fma_f32 v[34:35], v[40:41], v[40:41], v[52:53]
	v_add_f32_e32 v32, v32, v33
	v_add_f32_e32 v33, v48, v49
	v_add3_u32 v50, v36, v60, s20
	v_add3_u32 v51, v37, v59, s20
	v_pk_fma_f32 v[36:37], v[44:45], v[44:45], v[54:55]
	v_add_f32_e32 v34, v34, v35
	v_add_f32_e32 v32, v33, v32
	v_add_f32_e32 v35, v36, v37
	v_add_f32_e32 v32, v34, v32
	v_add_f32_e32 v32, v32, v35
	s_nop 1
	v_mov_b32_dpp v33, v32 quad_perm:[1,0,3,2] row_mask:0xf bank_mask:0xf
	v_and_b32_sdwa v61, v39, v16 dst_sel:DWORD dst_unused:UNUSED_PAD src0_sel:WORD_1 src1_sel:DWORD
	v_add3_u32 v39, v39, v61, s20
	v_and_b32_e32 v37, 0xffff0000, v39
	v_and_b32_e32 v35, 0xffff0000, v57
	s_waitcnt lgkmcnt(0)
; __device__ __forceinline__ unsigned pk2(float lo, float hi) { return f2bf(lo) | (f2bf(hi) << 16); }
; __device__ __forceinline__ float wave_sum(float v) {
; #pragma unroll
;     for (int o = 1; o < 64; o <<= 1) v += __shfl_xor(v, o);
;     return v;
; }
; __device__ __forceinline__ void nr_pass(bf16* X, const bf16* Y, const float* SSQ, float* ssqX, const float* g, float* out  , int gw, int NGW, int lane) {
;     ...
;             s2 += (v[j].x * v[j].x + v[j].y * v[j].y) + (v[j].z * v[j].z + v[j].w * v[j].w); }
;         if (out == nullptr) {
;             s2 = wave_sum(s2);
; #pragma unroll
;             for (int j = 0; j < 4; ++j) x8[64 * j] = (v2u){pk2(v[j].x, v[j].y), pk2(v[j].z, v[j].w)};
;             if (lane == 0) ssqX[r] = s2;
	v_add_f32_e32 v32, v32, v33
	s_nop 1
	v_mov_b32_dpp v33, v32 quad_perm:[2,3,0,1] row_mask:0xf bank_mask:0xf
	v_and_b32_sdwa v62, v38, v16 dst_sel:DWORD dst_unused:UNUSED_PAD src0_sel:WORD_1 src1_sel:DWORD
	v_and_b32_sdwa v66, v42, v16 dst_sel:DWORD dst_unused:UNUSED_PAD src0_sel:WORD_1 src1_sel:DWORD
	v_add3_u32 v38, v38, v62, s20
	v_and_b32_sdwa v67, v45, v16 dst_sel:DWORD dst_unused:UNUSED_PAD src0_sel:WORD_1 src1_sel:DWORD
	s_waitcnt lgkmcnt(0)
	v_add_f32_e32 v32, v32, v33
	s_nop 1
	v_mov_b32_dpp v39, v32 row_half_mirror row_mask:0xf bank_mask:0xf
	v_or_b32_sdwa v33, v35, v31 dst_sel:DWORD dst_unused:UNUSED_PAD src0_sel:DWORD src1_sel:WORD_1
	v_and_b32_sdwa v68, v44, v16 dst_sel:DWORD dst_unused:UNUSED_PAD src0_sel:WORD_1 src1_sel:DWORD
	v_and_b32_sdwa v69, v47, v16 dst_sel:DWORD dst_unused:UNUSED_PAD src0_sel:WORD_1 src1_sel:DWORD
	v_add3_u32 v34, v42, v66, s20
	s_waitcnt lgkmcnt(0)
	v_add_f32_e32 v31, v32, v39
	s_nop 1
	v_mov_b32_dpp v39, v31 row_mirror row_mask:0xf bank_mask:0xf
	v_and_b32_e32 v38, 0xffff0000, v38
	v_add3_u32 v42, v44, v68, s20
	v_add3_u32 v44, v45, v67, s20
	v_add3_u32 v45, v47, v69, s20
	s_waitcnt lgkmcnt(0)
	v_add_f32_e32 v31, v31, v39
	v_and_b32_e32 v47, 0xffff0000, v34
	v_or_b32_sdwa v34, v38, v50 dst_sel:DWORD dst_unused:UNUSED_PAD src0_sel:DWORD src1_sel:WORD_1
	v_mov_b32_e32 v38, v31
	s_nop 1
	v_permlane16_swap_b32_e32 v38, v31
	v_and_b32_sdwa v65, v43, v16 dst_sel:DWORD dst_unused:UNUSED_PAD src0_sel:WORD_1 src1_sel:DWORD
	v_and_b32_sdwa v63, v41, v16 dst_sel:DWORD dst_unused:UNUSED_PAD src0_sel:WORD_1 src1_sel:DWORD
	v_and_b32_sdwa v64, v40, v16 dst_sel:DWORD dst_unused:UNUSED_PAD src0_sel:WORD_1 src1_sel:DWORD
	v_add3_u32 v43, v43, v65, s20
	v_and_b32_e32 v36, 0xffff0000, v58
	v_add3_u32 v40, v40, v64, s20
	v_add3_u32 v41, v41, v63, s20
	v_and_b32_e32 v43, 0xffff0000, v43
	v_or_b32_sdwa v32, v36, v56 dst_sel:DWORD dst_unused:UNUSED_PAD src0_sel:DWORD src1_sel:WORD_1
	s_waitcnt lgkmcnt(0)
	v_add_f32_e32 v31, v31, v38
	v_or_b32_sdwa v35, v37, v51 dst_sel:DWORD dst_unused:UNUSED_PAD src0_sel:DWORD src1_sel:WORD_1
	v_or_b32_sdwa v37, v43, v41 dst_sel:DWORD dst_unused:UNUSED_PAD src0_sel:DWORD src1_sel:WORD_1
	v_or_b32_sdwa v36, v47, v40 dst_sel:DWORD dst_unused:UNUSED_PAD src0_sel:DWORD src1_sel:WORD_1
	global_store_dwordx2 v[14:15], v[32:33], off offset:-1024
	global_store_dwordx2 v[14:15], v[34:35], off offset:-512
	global_store_dwordx2 v[14:15], v[36:37], off
	v_mov_b32_e32 v32, v31
	s_nop 1
	v_permlane32_swap_b32_e32 v32, v31
	v_and_b32_sdwa v70, v46, v16 dst_sel:DWORD dst_unused:UNUSED_PAD src0_sel:WORD_1 src1_sel:DWORD
	v_add3_u32 v46, v46, v70, s20
	v_and_b32_e32 v33, 0xffff0000, v45
	v_and_b32_e32 v34, 0xffff0000, v46
	v_or_b32_sdwa v35, v33, v44 dst_sel:DWORD dst_unused:UNUSED_PAD src0_sel:DWORD src1_sel:WORD_1
	v_or_b32_sdwa v34, v34, v42 dst_sel:DWORD dst_unused:UNUSED_PAD src0_sel:DWORD src1_sel:WORD_1
	global_store_dwordx2 v[14:15], v[34:35], off offset:512
	s_and_saveexec_b64 s[0:1], vcc
	s_cbranch_execz .LBB0_743
	s_waitcnt lgkmcnt(0)
	v_add_f32_e32 v14, v31, v32
	global_store_dword v17, v14, s[8:9]
	s_branch .LBB0_743

; __device__ __forceinline__ float half_sum32(float v) {
; #pragma unroll
;     for (int o = 1; o < 32; o <<= 1) v += __shfl_xor(v, o);
;     return v;
; }
; __device__ __forceinline__ void nr_pass(bf16* X, const bf16* Y, const float* SSQ, float* ssqX, const float* g, float* out  , int gw, int NGW, int lane) {
;     ...
;     for (int r = gw; r < M_REAL; r += NGW) {
;         const float part = SSQ[(size_t)r * 32 + (lane & 31)];
;         const float s = rsqrtf(half_sum32(part) * (1.0f / 1024.0f) + EPS);
;         v2u* x8 = (v2u*)(X + (size_t)r * 1024) + lane; const v2u* y8 = (const v2u*)(Y + (size_t)r * 1024) + lane;
;         f32x4 v[4]; float s2 = 0.f;
; #pragma unroll
;         for (int j = 0; j < 4; ++j) { const v2u xv = x8[64 * j], yv = __builtin_nontemporal_load(&y8[64 * j]);
;             v[j].x = bflo(xv.x) + bflo(yv.x) * s * gv[j].x; v[j].y = bfhi(xv.x) + bfhi(yv.x) * s * gv[j].y;
;             v[j].z = bflo(xv.y) + bflo(yv.y) * s * gv[j].z; v[j].w = bfhi(xv.y) + bfhi(yv.y) * s * gv[j].w;
;             s2 += (v[j].x * v[j].x + v[j].y * v[j].y) + (v[j].z * v[j].z + v[j].w * v[j].w); }
.LBB0_956:
	v_lshl_add_u64 v[34:35], s[4:5], 0, v[16:17]
	s_waitcnt lgkmcnt(0)
	v_lshl_add_u64 v[32:33], s[4:5], 0, v[18:19]
	v_add_co_u32_e64 v14, s[0:1], s16, v34
	s_nop 1
	v_addc_co_u32_e64 v15, s[0:1], 0, v35, s[0:1]
	global_load_dword v31, v[32:33], off
	global_load_dwordx2 v[36:37], v[14:15], off
	v_add_co_u32_e64 v32, s[0:1], s17, v34
	s_waitcnt vmcnt(1)
	s_nop 1
	v_mov_b32_dpp v56, v31 quad_perm:[1,0,3,2] row_mask:0xf bank_mask:0xf
	v_addc_co_u32_e64 v33, s[0:1], 0, v35, s[0:1]
	global_load_dwordx2 v[34:35], v[32:33], off nt
	global_load_dwordx2 v[38:39], v[14:15], off offset:512
	global_load_dwordx2 v[40:41], v[32:33], off offset:512 nt
	global_load_dwordx2 v[42:43], v[14:15], off offset:1024
	global_load_dwordx2 v[44:45], v[32:33], off offset:1024 nt
	global_load_dwordx2 v[46:47], v[14:15], off offset:1536
	global_load_dwordx2 v[48:49], v[32:33], off offset:1536 nt
	s_waitcnt vmcnt(7)
	v_lshlrev_b32_e32 v33, 16, v37
	s_waitcnt lgkmcnt(0)
	v_add_f32_e32 v31, v31, v56
	s_nop 1
	v_mov_b32_dpp v56, v31 quad_perm:[2,3,0,1] row_mask:0xf bank_mask:0xf
	v_lshlrev_b32_e32 v32, 16, v36
	v_and_b32_e32 v37, 0xffff0000, v37
	v_and_b32_e32 v36, 0xffff0000, v36
	s_waitcnt lgkmcnt(0)
	v_add_f32_e32 v31, v31, v56
	s_nop 1
	v_mov_b32_dpp v60, v31 row_half_mirror row_mask:0xf bank_mask:0xf
	s_waitcnt lgkmcnt(0)
	v_add_f32_e32 v31, v31, v60
	s_nop 1
	v_mov_b32_dpp v60, v31 row_mirror row_mask:0xf bank_mask:0xf
	s_waitcnt lgkmcnt(0)
	v_add_f32_e32 v31, v31, v60
	v_mov_b32_e32 v64, v31
	s_nop 1
	v_permlane16_swap_b32_e32 v64, v31
	s_waitcnt lgkmcnt(0)
	v_add_f32_e32 v31, v31, v64
	v_fmamk_f32 v31, v31, 0x3a800000, v22
	v_mul_f32_e32 v64, 0x4b800000, v31
	v_cmp_gt_f32_e64 s[0:1], s15, v31
	s_waitcnt vmcnt(6)
	v_lshlrev_b32_e32 v51, 16, v35
	v_cndmask_b32_e64 v31, v31, v64, s[0:1]
	v_rsq_f32_e32 v31, v31
	v_lshlrev_b32_e32 v50, 16, v34
	v_and_b32_e32 v35, 0xffff0000, v35
	v_and_b32_e32 v34, 0xffff0000, v34
	v_mul_f32_e32 v64, 0x45800000, v31
	s_waitcnt vmcnt(4)
	v_lshlrev_b32_e32 v55, 16, v41
	v_lshlrev_b32_e32 v54, 16, v40
	v_and_b32_e32 v41, 0xffff0000, v41
	v_and_b32_e32 v40, 0xffff0000, v40
	v_cndmask_b32_e64 v64, v31, v64, s[0:1]
	v_lshlrev_b32_e32 v53, 16, v39
	v_lshlrev_b32_e32 v52, 16, v38
	v_and_b32_e32 v39, 0xffff0000, v39
	v_and_b32_e32 v38, 0xffff0000, v38
	s_waitcnt vmcnt(2)
	v_lshlrev_b32_e32 v59, 16, v45
	v_lshlrev_b32_e32 v58, 16, v44
	v_and_b32_e32 v45, 0xffff0000, v45
	v_and_b32_e32 v44, 0xffff0000, v44
	s_waitcnt vmcnt(0)
	v_lshlrev_b32_e32 v63, 16, v49
	v_lshlrev_b32_e32 v62, 16, v48
	v_and_b32_e32 v49, 0xffff0000, v49
	v_and_b32_e32 v48, 0xffff0000, v48
	v_pk_mul_f32 v[50:51], v[64:65], v[50:51] op_sel_hi:[0,1]
	v_pk_mul_f32 v[34:35], v[64:65], v[34:35] op_sel_hi:[0,1]
	v_pk_mul_f32 v[40:41], v[64:65], v[40:41] op_sel_hi:[0,1]
	v_lshlrev_b32_e32 v57, 16, v43
	v_lshlrev_b32_e32 v56, 16, v42
	v_and_b32_e32 v43, 0xffff0000, v43
	v_and_b32_e32 v42, 0xffff0000, v42
	v_lshlrev_b32_e32 v61, 16, v47
	v_lshlrev_b32_e32 v60, 16, v46
	v_and_b32_e32 v47, 0xffff0000, v47
	v_and_b32_e32 v46, 0xffff0000, v46
	v_pk_mul_f32 v[54:55], v[64:65], v[54:55] op_sel_hi:[0,1]
	v_pk_mul_f32 v[58:59], v[64:65], v[58:59] op_sel_hi:[0,1]
	v_pk_mul_f32 v[44:45], v[64:65], v[44:45] op_sel_hi:[0,1]
	v_pk_mul_f32 v[48:49], v[64:65], v[48:49] op_sel_hi:[0,1]
	v_pk_fma_f32 v[32:33], v[0:1], v[50:51], v[32:33]
	v_pk_fma_f32 v[34:35], v[20:21], v[34:35], v[36:37]
	v_pk_fma_f32 v[38:39], v[2:3], v[40:41], v[38:39]
	v_pk_fma_f32 v[36:37], v[4:5], v[54:55], v[52:53]
	v_pk_fma_f32 v[40:41], v[8:9], v[58:59], v[56:57]
	v_pk_fma_f32 v[42:43], v[6:7], v[44:45], v[42:43]
	v_pk_fma_f32 v[46:47], v[10:11], v[48:49], v[46:47]
	v_pk_mul_f32 v[48:49], v[34:35], v[34:35]
	v_and_b32_sdwa v31, v33, v30 dst_sel:DWORD dst_unused:UNUSED_PAD src0_sel:WORD_1 src1_sel:DWORD
	v_and_b32_sdwa v56, v32, v30 dst_sel:DWORD dst_unused:UNUSED_PAD src0_sel:WORD_1 src1_sel:DWORD
	v_pk_mul_f32 v[50:51], v[38:39], v[38:39]
	v_pk_mul_f32 v[62:63], v[64:65], v[62:63] op_sel_hi:[0,1]
	v_and_b32_sdwa v57, v35, v30 dst_sel:DWORD dst_unused:UNUSED_PAD src0_sel:WORD_1 src1_sel:DWORD
	v_and_b32_sdwa v58, v34, v30 dst_sel:DWORD dst_unused:UNUSED_PAD src0_sel:WORD_1 src1_sel:DWORD
	v_pk_mul_f32 v[52:53], v[42:43], v[42:43]
	v_pk_fma_f32 v[48:49], v[32:33], v[32:33], v[48:49]
	v_add3_u32 v56, v32, v56, s18
	v_add3_u32 v31, v33, v31, s18
	v_pk_fma_f32 v[32:33], v[36:37], v[36:37], v[50:51]
	v_pk_fma_f32 v[44:45], v[12:13], v[62:63], v[60:61]
	v_and_b32_sdwa v59, v37, v30 dst_sel:DWORD dst_unused:UNUSED_PAD src0_sel:WORD_1 src1_sel:DWORD
	v_and_b32_sdwa v60, v36, v30 dst_sel:DWORD dst_unused:UNUSED_PAD src0_sel:WORD_1 src1_sel:DWORD
	v_pk_mul_f32 v[54:55], v[46:47], v[46:47]
	v_add3_u32 v57, v35, v57, s18
	v_add3_u32 v58, v34, v58, s18
	v_pk_fma_f32 v[34:35], v[40:41], v[40:41], v[52:53]
	v_add_f32_e32 v32, v32, v33
	v_add_f32_e32 v33, v48, v49
	v_add3_u32 v50, v36, v60, s18
	v_add3_u32 v51, v37, v59, s18
	v_pk_fma_f32 v[36:37], v[44:45], v[44:45], v[54:55]
	v_add_f32_e32 v34, v34, v35
	v_add_f32_e32 v32, v33, v32
	v_add_f32_e32 v35, v36, v37
	v_add_f32_e32 v32, v34, v32
	v_add_f32_e32 v32, v32, v35
	s_nop 1
	v_mov_b32_dpp v33, v32 quad_perm:[1,0,3,2] row_mask:0xf bank_mask:0xf
	v_and_b32_sdwa v61, v39, v30 dst_sel:DWORD dst_unused:UNUSED_PAD src0_sel:WORD_1 src1_sel:DWORD
	v_add3_u32 v39, v39, v61, s18
	v_and_b32_e32 v37, 0xffff0000, v39
	v_and_b32_e32 v35, 0xffff0000, v57
	s_waitcnt lgkmcnt(0)
; __device__ __forceinline__ unsigned pk2(float lo, float hi) { return f2bf(lo) | (f2bf(hi) << 16); }
; __device__ __forceinline__ float wave_sum(float v) {
; #pragma unroll
;     for (int o = 1; o < 64; o <<= 1) v += __shfl_xor(v, o);
;     return v;
; }
; __device__ __forceinline__ void nr_pass(bf16* X, const bf16* Y, const float* SSQ, float* ssqX, const float* g, float* out  , int gw, int NGW, int lane) {
;     ...
;             s2 += (v[j].x * v[j].x + v[j].y * v[j].y) + (v[j].z * v[j].z + v[j].w * v[j].w); }
;         if (out == nullptr) {
;             s2 = wave_sum(s2);
; #pragma unroll
;             for (int j = 0; j < 4; ++j) x8[64 * j] = (v2u){pk2(v[j].x, v[j].y), pk2(v[j].z, v[j].w)};
;             if (lane == 0) ssqX[r] = s2;
	v_add_f32_e32 v32, v32, v33
	s_nop 1
	v_mov_b32_dpp v33, v32 quad_perm:[2,3,0,1] row_mask:0xf bank_mask:0xf
	v_and_b32_sdwa v62, v38, v30 dst_sel:DWORD dst_unused:UNUSED_PAD src0_sel:WORD_1 src1_sel:DWORD
	v_and_b32_sdwa v66, v42, v30 dst_sel:DWORD dst_unused:UNUSED_PAD src0_sel:WORD_1 src1_sel:DWORD
	v_add3_u32 v38, v38, v62, s18
	v_and_b32_sdwa v67, v45, v30 dst_sel:DWORD dst_unused:UNUSED_PAD src0_sel:WORD_1 src1_sel:DWORD
	s_waitcnt lgkmcnt(0)
	v_add_f32_e32 v32, v32, v33
	s_nop 1
	v_mov_b32_dpp v39, v32 row_half_mirror row_mask:0xf bank_mask:0xf
	v_or_b32_sdwa v33, v35, v31 dst_sel:DWORD dst_unused:UNUSED_PAD src0_sel:DWORD src1_sel:WORD_1
	v_and_b32_sdwa v68, v44, v30 dst_sel:DWORD dst_unused:UNUSED_PAD src0_sel:WORD_1 src1_sel:DWORD
	v_and_b32_sdwa v69, v47, v30 dst_sel:DWORD dst_unused:UNUSED_PAD src0_sel:WORD_1 src1_sel:DWORD
	v_add3_u32 v34, v42, v66, s18
	s_waitcnt lgkmcnt(0)
	v_add_f32_e32 v31, v32, v39
	s_nop 1
	v_mov_b32_dpp v39, v31 row_mirror row_mask:0xf bank_mask:0xf
	v_and_b32_e32 v38, 0xffff0000, v38
	v_add3_u32 v42, v44, v68, s18
	v_add3_u32 v44, v45, v67, s18
	v_add3_u32 v45, v47, v69, s18
	s_waitcnt lgkmcnt(0)
	v_add_f32_e32 v31, v31, v39
	v_and_b32_e32 v47, 0xffff0000, v34
	v_or_b32_sdwa v34, v38, v50 dst_sel:DWORD dst_unused:UNUSED_PAD src0_sel:DWORD src1_sel:WORD_1
	v_mov_b32_e32 v38, v31
	s_nop 1
	v_permlane16_swap_b32_e32 v38, v31
	v_and_b32_sdwa v65, v43, v30 dst_sel:DWORD dst_unused:UNUSED_PAD src0_sel:WORD_1 src1_sel:DWORD
	v_and_b32_sdwa v63, v41, v30 dst_sel:DWORD dst_unused:UNUSED_PAD src0_sel:WORD_1 src1_sel:DWORD
	v_and_b32_sdwa v64, v40, v30 dst_sel:DWORD dst_unused:UNUSED_PAD src0_sel:WORD_1 src1_sel:DWORD
	v_add3_u32 v43, v43, v65, s18
	v_and_b32_e32 v36, 0xffff0000, v58
	v_add3_u32 v40, v40, v64, s18
	v_add3_u32 v41, v41, v63, s18
	v_and_b32_e32 v43, 0xffff0000, v43
	v_or_b32_sdwa v32, v36, v56 dst_sel:DWORD dst_unused:UNUSED_PAD src0_sel:DWORD src1_sel:WORD_1
	s_waitcnt lgkmcnt(0)
	v_add_f32_e32 v31, v31, v38
	v_or_b32_sdwa v35, v37, v51 dst_sel:DWORD dst_unused:UNUSED_PAD src0_sel:DWORD src1_sel:WORD_1
	v_or_b32_sdwa v37, v43, v41 dst_sel:DWORD dst_unused:UNUSED_PAD src0_sel:DWORD src1_sel:WORD_1
	v_or_b32_sdwa v36, v47, v40 dst_sel:DWORD dst_unused:UNUSED_PAD src0_sel:DWORD src1_sel:WORD_1
	global_store_dwordx2 v[14:15], v[32:33], off
	global_store_dwordx2 v[14:15], v[34:35], off offset:512
	global_store_dwordx2 v[14:15], v[36:37], off offset:1024
	v_mov_b32_e32 v32, v31
	s_nop 1
	v_permlane32_swap_b32_e32 v32, v31
	v_and_b32_sdwa v70, v46, v30 dst_sel:DWORD dst_unused:UNUSED_PAD src0_sel:WORD_1 src1_sel:DWORD
	v_add3_u32 v46, v46, v70, s18
	v_and_b32_e32 v33, 0xffff0000, v45
	v_and_b32_e32 v34, 0xffff0000, v46
	v_or_b32_sdwa v35, v33, v44 dst_sel:DWORD dst_unused:UNUSED_PAD src0_sel:DWORD src1_sel:WORD_1
	v_or_b32_sdwa v34, v34, v42 dst_sel:DWORD dst_unused:UNUSED_PAD src0_sel:DWORD src1_sel:WORD_1
	global_store_dwordx2 v[14:15], v[34:35], off offset:1536
	s_and_saveexec_b64 s[0:1], vcc
	s_cbranch_execz .LBB0_955
	s_add_u32 s22, s4, s19
	s_waitcnt lgkmcnt(0)
	v_add_f32_e32 v14, v31, v32
	s_addc_u32 s23, s5, s20
	global_store_dword v23, v14, s[22:23]
	s_branch .LBB0_955

; __device__ __forceinline__ float half_sum32(float v) {
; #pragma unroll
;     for (int o = 1; o < 32; o <<= 1) v += __shfl_xor(v, o);
;     return v;
; }
; __device__ __forceinline__ void nr_pass(bf16* X, const bf16* Y, const float* SSQ, float* ssqX, const float* g, float* out  , int gw, int NGW, int lane) {
;     ...
;     for (int r = gw; r < M_REAL; r += NGW) {
;         const float part = SSQ[(size_t)r * 32 + (lane & 31)];
;         const float s = rsqrtf(half_sum32(part) * (1.0f / 1024.0f) + EPS);
;         v2u* x8 = (v2u*)(X + (size_t)r * 1024) + lane; const v2u* y8 = (const v2u*)(Y + (size_t)r * 1024) + lane;
;         f32x4 v[4]; float s2 = 0.f;
; #pragma unroll
;         for (int j = 0; j < 4; ++j) { const v2u xv = x8[64 * j], yv = __builtin_nontemporal_load(&y8[64 * j]);
;             v[j].x = bflo(xv.x) + bflo(yv.x) * s * gv[j].x; v[j].y = bfhi(xv.x) + bfhi(yv.x) * s * gv[j].y;
;             v[j].z = bflo(xv.y) + bflo(yv.y) * s * gv[j].z; v[j].w = bfhi(xv.y) + bfhi(yv.y) * s * gv[j].w;
;             s2 += (v[j].x * v[j].x + v[j].y * v[j].y) + (v[j].z * v[j].z + v[j].w * v[j].w); }
.LBB0_1544:
	global_load_dword v31, v[18:19], off
	v_lshl_add_u64 v[14:15], s[14:15], 0, v[20:21]
	v_lshl_add_u64 v[34:35], s[2:3], 0, v[20:21]
	s_waitcnt lgkmcnt(0)
	global_load_dwordx2 v[32:33], v[14:15], off offset:-1024
	global_load_dwordx2 v[36:37], v[34:35], off nt
	global_load_dwordx2 v[38:39], v[14:15], off offset:-512
	global_load_dwordx2 v[40:41], v[34:35], off offset:512 nt
	global_load_dwordx2 v[42:43], v[14:15], off
	global_load_dwordx2 v[44:45], v[34:35], off offset:1024 nt
	global_load_dwordx2 v[46:47], v[14:15], off offset:512
	global_load_dwordx2 v[48:49], v[34:35], off offset:1536 nt
	s_waitcnt vmcnt(6)
	v_lshlrev_b32_e32 v51, 16, v37
	v_lshlrev_b32_e32 v50, 16, v36
	s_nop 1
	v_mov_b32_dpp v56, v31 quad_perm:[1,0,3,2] row_mask:0xf bank_mask:0xf
	v_and_b32_e32 v37, 0xffff0000, v37
	v_and_b32_e32 v36, 0xffff0000, v36
	s_waitcnt vmcnt(4)
	v_lshlrev_b32_e32 v55, 16, v41
	v_lshlrev_b32_e32 v54, 16, v40
	s_waitcnt lgkmcnt(0)
	v_add_f32_e32 v31, v31, v56
	s_nop 1
	v_mov_b32_dpp v56, v31 quad_perm:[2,3,0,1] row_mask:0xf bank_mask:0xf
	v_and_b32_e32 v41, 0xffff0000, v41
	v_and_b32_e32 v40, 0xffff0000, v40
	v_lshlrev_b32_e32 v35, 16, v33
	v_lshlrev_b32_e32 v34, 16, v32
	s_waitcnt lgkmcnt(0)
	v_add_f32_e32 v31, v31, v56
	s_nop 1
	v_mov_b32_dpp v60, v31 row_half_mirror row_mask:0xf bank_mask:0xf
	v_and_b32_e32 v33, 0xffff0000, v33
	v_and_b32_e32 v32, 0xffff0000, v32
	v_lshlrev_b32_e32 v53, 16, v39
	v_lshlrev_b32_e32 v52, 16, v38
	s_waitcnt lgkmcnt(0)
	v_add_f32_e32 v31, v31, v60
	s_nop 1
	v_mov_b32_dpp v60, v31 row_mirror row_mask:0xf bank_mask:0xf
	v_and_b32_e32 v39, 0xffff0000, v39
	v_and_b32_e32 v38, 0xffff0000, v38
	s_waitcnt vmcnt(2)
	v_lshlrev_b32_e32 v59, 16, v45
	v_lshlrev_b32_e32 v58, 16, v44
	s_waitcnt lgkmcnt(0)
	v_add_f32_e32 v31, v31, v60
	v_mov_b32_e32 v64, v31
	s_nop 1
	v_permlane16_swap_b32_e32 v64, v31
	v_and_b32_e32 v45, 0xffff0000, v45
	v_and_b32_e32 v44, 0xffff0000, v44
	s_waitcnt vmcnt(0)
	v_lshlrev_b32_e32 v63, 16, v49
	v_lshlrev_b32_e32 v62, 16, v48
	s_waitcnt lgkmcnt(0)
	v_add_f32_e32 v31, v31, v64
	v_fmamk_f32 v31, v31, 0x3a800000, v24
	v_mul_f32_e32 v64, 0x4b800000, v31
	v_cmp_gt_f32_e64 s[0:1], s19, v31
	v_and_b32_e32 v49, 0xffff0000, v49
	v_and_b32_e32 v48, 0xffff0000, v48
	v_cndmask_b32_e64 v31, v31, v64, s[0:1]
	v_rsq_f32_e32 v31, v31
	v_lshlrev_b32_e32 v57, 16, v43
	v_lshlrev_b32_e32 v56, 16, v42
	v_and_b32_e32 v43, 0xffff0000, v43
	v_mul_f32_e32 v64, 0x45800000, v31
	v_cndmask_b32_e64 v64, v31, v64, s[0:1]
	v_pk_mul_f32 v[36:37], v[64:65], v[36:37] op_sel_hi:[0,1]
	v_pk_mul_f32 v[40:41], v[64:65], v[40:41] op_sel_hi:[0,1]
	v_and_b32_e32 v42, 0xffff0000, v42
	v_lshlrev_b32_e32 v61, 16, v47
	v_lshlrev_b32_e32 v60, 16, v46
	v_and_b32_e32 v47, 0xffff0000, v47
	v_and_b32_e32 v46, 0xffff0000, v46
	v_pk_mul_f32 v[50:51], v[64:65], v[50:51] op_sel_hi:[0,1]
	v_pk_mul_f32 v[54:55], v[64:65], v[54:55] op_sel_hi:[0,1]
	v_pk_mul_f32 v[58:59], v[64:65], v[58:59] op_sel_hi:[0,1]
	v_pk_mul_f32 v[44:45], v[64:65], v[44:45] op_sel_hi:[0,1]
	v_pk_mul_f32 v[48:49], v[64:65], v[48:49] op_sel_hi:[0,1]
	v_pk_fma_f32 v[32:33], v[10:11], v[36:37], v[32:33]
	v_pk_fma_f32 v[38:39], v[22:23], v[40:41], v[38:39]
	v_pk_fma_f32 v[34:35], v[12:13], v[50:51], v[34:35]
	v_pk_fma_f32 v[36:37], v[0:1], v[54:55], v[52:53]
	v_pk_fma_f32 v[40:41], v[4:5], v[58:59], v[56:57]
	v_pk_fma_f32 v[42:43], v[2:3], v[44:45], v[42:43]
	v_pk_fma_f32 v[46:47], v[6:7], v[48:49], v[46:47]
	v_pk_mul_f32 v[48:49], v[32:33], v[32:33]
	v_and_b32_sdwa v57, v33, v16 dst_sel:DWORD dst_unused:UNUSED_PAD src0_sel:WORD_1 src1_sel:DWORD
	v_and_b32_sdwa v58, v32, v16 dst_sel:DWORD dst_unused:UNUSED_PAD src0_sel:WORD_1 src1_sel:DWORD
	v_pk_mul_f32 v[50:51], v[38:39], v[38:39]
	v_pk_mul_f32 v[62:63], v[64:65], v[62:63] op_sel_hi:[0,1]
	v_and_b32_sdwa v31, v35, v16 dst_sel:DWORD dst_unused:UNUSED_PAD src0_sel:WORD_1 src1_sel:DWORD
	v_and_b32_sdwa v56, v34, v16 dst_sel:DWORD dst_unused:UNUSED_PAD src0_sel:WORD_1 src1_sel:DWORD
	v_pk_mul_f32 v[52:53], v[42:43], v[42:43]
	v_pk_fma_f32 v[48:49], v[34:35], v[34:35], v[48:49]
	v_add3_u32 v57, v33, v57, s7
	v_add3_u32 v58, v32, v58, s7
	v_pk_fma_f32 v[32:33], v[36:37], v[36:37], v[50:51]
	v_pk_fma_f32 v[44:45], v[8:9], v[62:63], v[60:61]
	v_and_b32_sdwa v59, v37, v16 dst_sel:DWORD dst_unused:UNUSED_PAD src0_sel:WORD_1 src1_sel:DWORD
	v_and_b32_sdwa v60, v36, v16 dst_sel:DWORD dst_unused:UNUSED_PAD src0_sel:WORD_1 src1_sel:DWORD
	v_pk_mul_f32 v[54:55], v[46:47], v[46:47]
	v_add3_u32 v56, v34, v56, s7
	v_add3_u32 v31, v35, v31, s7
	v_pk_fma_f32 v[34:35], v[40:41], v[40:41], v[52:53]
	v_add_f32_e32 v32, v32, v33
	v_add_f32_e32 v33, v48, v49
	v_add3_u32 v50, v36, v60, s7
	v_add3_u32 v51, v37, v59, s7
	v_pk_fma_f32 v[36:37], v[44:45], v[44:45], v[54:55]
	v_add_f32_e32 v34, v34, v35
	v_add_f32_e32 v32, v33, v32
	v_add_f32_e32 v35, v36, v37
	v_add_f32_e32 v32, v34, v32
	v_add_f32_e32 v32, v32, v35
	s_nop 1
	v_mov_b32_dpp v33, v32 quad_perm:[1,0,3,2] row_mask:0xf bank_mask:0xf
	v_and_b32_sdwa v61, v39, v16 dst_sel:DWORD dst_unused:UNUSED_PAD src0_sel:WORD_1 src1_sel:DWORD
	v_add3_u32 v39, v39, v61, s7
	v_and_b32_e32 v37, 0xffff0000, v39
	v_and_b32_e32 v35, 0xffff0000, v57
	s_waitcnt lgkmcnt(0)
; __device__ __forceinline__ unsigned pk2(float lo, float hi) { return f2bf(lo) | (f2bf(hi) << 16); }
; __device__ __forceinline__ float wave_sum(float v) {
; #pragma unroll
;     for (int o = 1; o < 64; o <<= 1) v += __shfl_xor(v, o);
;     return v;
; }
; __device__ __forceinline__ void nr_pass(bf16* X, const bf16* Y, const float* SSQ, float* ssqX, const float* g, float* out  , int gw, int NGW, int lane) {
;     ...
;             s2 += (v[j].x * v[j].x + v[j].y * v[j].y) + (v[j].z * v[j].z + v[j].w * v[j].w); }
;         if (out == nullptr) {
;             s2 = wave_sum(s2);
; #pragma unroll
;             for (int j = 0; j < 4; ++j) x8[64 * j] = (v2u){pk2(v[j].x, v[j].y), pk2(v[j].z, v[j].w)};
;             if (lane == 0) ssqX[r] = s2;
	v_add_f32_e32 v32, v32, v33
	s_nop 1
	v_mov_b32_dpp v33, v32 quad_perm:[2,3,0,1] row_mask:0xf bank_mask:0xf
	v_and_b32_sdwa v62, v38, v16 dst_sel:DWORD dst_unused:UNUSED_PAD src0_sel:WORD_1 src1_sel:DWORD
	v_and_b32_sdwa v66, v42, v16 dst_sel:DWORD dst_unused:UNUSED_PAD src0_sel:WORD_1 src1_sel:DWORD
	v_add3_u32 v38, v38, v62, s7
	v_and_b32_sdwa v67, v45, v16 dst_sel:DWORD dst_unused:UNUSED_PAD src0_sel:WORD_1 src1_sel:DWORD
	s_waitcnt lgkmcnt(0)
	v_add_f32_e32 v32, v32, v33
	s_nop 1
	v_mov_b32_dpp v39, v32 row_half_mirror row_mask:0xf bank_mask:0xf
	v_or_b32_sdwa v33, v35, v31 dst_sel:DWORD dst_unused:UNUSED_PAD src0_sel:DWORD src1_sel:WORD_1
	v_and_b32_sdwa v68, v44, v16 dst_sel:DWORD dst_unused:UNUSED_PAD src0_sel:WORD_1 src1_sel:DWORD
	v_and_b32_sdwa v69, v47, v16 dst_sel:DWORD dst_unused:UNUSED_PAD src0_sel:WORD_1 src1_sel:DWORD
	v_add3_u32 v34, v42, v66, s7
	s_waitcnt lgkmcnt(0)
	v_add_f32_e32 v31, v32, v39
	s_nop 1
	v_mov_b32_dpp v39, v31 row_mirror row_mask:0xf bank_mask:0xf
	v_and_b32_e32 v38, 0xffff0000, v38
	v_add3_u32 v42, v44, v68, s7
	v_add3_u32 v44, v45, v67, s7
	v_add3_u32 v45, v47, v69, s7
	s_waitcnt lgkmcnt(0)
	v_add_f32_e32 v31, v31, v39
	v_and_b32_e32 v47, 0xffff0000, v34
	v_or_b32_sdwa v34, v38, v50 dst_sel:DWORD dst_unused:UNUSED_PAD src0_sel:DWORD src1_sel:WORD_1
	v_mov_b32_e32 v38, v31
	s_nop 1
	v_permlane16_swap_b32_e32 v38, v31
	v_and_b32_sdwa v65, v43, v16 dst_sel:DWORD dst_unused:UNUSED_PAD src0_sel:WORD_1 src1_sel:DWORD
	v_and_b32_sdwa v63, v41, v16 dst_sel:DWORD dst_unused:UNUSED_PAD src0_sel:WORD_1 src1_sel:DWORD
	v_and_b32_sdwa v64, v40, v16 dst_sel:DWORD dst_unused:UNUSED_PAD src0_sel:WORD_1 src1_sel:DWORD
	v_add3_u32 v43, v43, v65, s7
	v_and_b32_e32 v36, 0xffff0000, v58
	v_add3_u32 v40, v40, v64, s7
	v_add3_u32 v41, v41, v63, s7
	v_and_b32_e32 v43, 0xffff0000, v43
	v_or_b32_sdwa v32, v36, v56 dst_sel:DWORD dst_unused:UNUSED_PAD src0_sel:DWORD src1_sel:WORD_1
	s_waitcnt lgkmcnt(0)
	v_add_f32_e32 v31, v31, v38
	v_or_b32_sdwa v35, v37, v51 dst_sel:DWORD dst_unused:UNUSED_PAD src0_sel:DWORD src1_sel:WORD_1
	v_or_b32_sdwa v37, v43, v41 dst_sel:DWORD dst_unused:UNUSED_PAD src0_sel:DWORD src1_sel:WORD_1
	v_or_b32_sdwa v36, v47, v40 dst_sel:DWORD dst_unused:UNUSED_PAD src0_sel:DWORD src1_sel:WORD_1
	global_store_dwordx2 v[14:15], v[32:33], off offset:-1024
	global_store_dwordx2 v[14:15], v[34:35], off offset:-512
	global_store_dwordx2 v[14:15], v[36:37], off
	v_mov_b32_e32 v32, v31
	s_nop 1
	v_permlane32_swap_b32_e32 v32, v31
	v_and_b32_sdwa v70, v46, v16 dst_sel:DWORD dst_unused:UNUSED_PAD src0_sel:WORD_1 src1_sel:DWORD
	v_add3_u32 v46, v46, v70, s7
	v_and_b32_e32 v33, 0xffff0000, v45
	v_and_b32_e32 v34, 0xffff0000, v46
	v_or_b32_sdwa v35, v33, v44 dst_sel:DWORD dst_unused:UNUSED_PAD src0_sel:DWORD src1_sel:WORD_1
	v_or_b32_sdwa v34, v34, v42 dst_sel:DWORD dst_unused:UNUSED_PAD src0_sel:DWORD src1_sel:WORD_1
	global_store_dwordx2 v[14:15], v[34:35], off offset:512
	s_and_saveexec_b64 s[0:1], vcc
	s_cbranch_execz .LBB0_1543
	s_waitcnt lgkmcnt(0)
	v_add_f32_e32 v14, v31, v32
	global_store_dword v17, v14, s[8:9]
	s_branch .LBB0_1543

; __device__ __forceinline__ float half_sum32(float v) {
; #pragma unroll
;     for (int o = 1; o < 32; o <<= 1) v += __shfl_xor(v, o);
;     return v;
; }
; __device__ __forceinline__ void nr_pass(bf16* X, const bf16* Y, const float* SSQ, float* ssqX, const float* g, float* out  , int gw, int NGW, int lane) {
;     ...
;     for (int r = gw; r < M_REAL; r += NGW) {
;         const float part = SSQ[(size_t)r * 32 + (lane & 31)];
;         const float s = rsqrtf(half_sum32(part) * (1.0f / 1024.0f) + EPS);
;         v2u* x8 = (v2u*)(X + (size_t)r * 1024) + lane; const v2u* y8 = (const v2u*)(Y + (size_t)r * 1024) + lane;
;         f32x4 v[4]; float s2 = 0.f;
; #pragma unroll
;         for (int j = 0; j < 4; ++j) { const v2u xv = x8[64 * j], yv = __builtin_nontemporal_load(&y8[64 * j]);
;             v[j].x = bflo(xv.x) + bflo(yv.x) * s * gv[j].x; v[j].y = bfhi(xv.x) + bfhi(yv.x) * s * gv[j].y;
;             v[j].z = bflo(xv.y) + bflo(yv.y) * s * gv[j].z; v[j].w = bfhi(xv.y) + bfhi(yv.y) * s * gv[j].w;
;             s2 += (v[j].x * v[j].x + v[j].y * v[j].y) + (v[j].z * v[j].z + v[j].w * v[j].w); }
.LBB0_1757:
	s_waitcnt lgkmcnt(0)
	v_lshl_add_u64 v[14:15], s[92:93], 0, v[18:19]
	v_lshl_add_u64 v[24:25], s[92:93], 0, v[20:21]
	v_add_co_u32_e32 v26, vcc, s7, v14
	s_nop 1
	v_addc_co_u32_e32 v27, vcc, 0, v15, vcc
	global_load_dword v49, v[24:25], off
	global_load_dwordx2 v[28:29], v[26:27], off
	v_add_co_u32_e32 v24, vcc, s34, v14
	s_waitcnt vmcnt(1)
	s_nop 1
	v_mov_b32_dpp v58, v49 quad_perm:[1,0,3,2] row_mask:0xf bank_mask:0xf
	v_addc_co_u32_e32 v25, vcc, 0, v15, vcc
	global_load_dwordx2 v[30:31], v[24:25], off nt
	global_load_dwordx2 v[32:33], v[26:27], off offset:512
	global_load_dwordx2 v[34:35], v[24:25], off offset:512 nt
	global_load_dwordx2 v[36:37], v[26:27], off offset:1024
	global_load_dwordx2 v[38:39], v[24:25], off offset:1024 nt
	global_load_dwordx2 v[50:51], v[26:27], off offset:1536
	global_load_dwordx2 v[52:53], v[24:25], off offset:1536 nt
	s_waitcnt vmcnt(7)
	v_lshlrev_b32_e32 v25, 16, v29
	s_waitcnt lgkmcnt(0)
	v_add_f32_e32 v49, v49, v58
	s_nop 1
	v_mov_b32_dpp v58, v49 quad_perm:[2,3,0,1] row_mask:0xf bank_mask:0xf
	v_lshlrev_b32_e32 v24, 16, v28
	v_and_b32_e32 v29, 0xffff0000, v29
	v_and_b32_e32 v28, 0xffff0000, v28
	s_and_b64 vcc, exec, s[12:13]
	s_waitcnt lgkmcnt(0)
	v_add_f32_e32 v49, v49, v58
	s_nop 1
	v_mov_b32_dpp v62, v49 row_half_mirror row_mask:0xf bank_mask:0xf
	s_waitcnt lgkmcnt(0)
	v_add_f32_e32 v49, v49, v62
	s_nop 1
	v_mov_b32_dpp v64, v49 row_mirror row_mask:0xf bank_mask:0xf
	s_waitcnt lgkmcnt(0)
	v_add_f32_e32 v49, v49, v64
	v_mov_b32_e32 v66, v49
	s_nop 1
	v_permlane16_swap_b32_e32 v66, v49
	s_waitcnt lgkmcnt(0)
	v_add_f32_e32 v49, v49, v66
	v_fmamk_f32 v49, v49, 0x3a800000, v40
	v_mul_f32_e32 v66, 0x4b800000, v49
	v_cmp_gt_f32_e64 s[0:1], s29, v49
	s_waitcnt vmcnt(6)
	v_lshlrev_b32_e32 v27, 16, v31
	v_cndmask_b32_e64 v49, v49, v66, s[0:1]
	v_rsq_f32_e32 v49, v49
	v_lshlrev_b32_e32 v26, 16, v30
	v_and_b32_e32 v31, 0xffff0000, v31
	v_and_b32_e32 v30, 0xffff0000, v30
	v_mul_f32_e32 v66, 0x45800000, v49
	s_waitcnt vmcnt(4)
	v_lshlrev_b32_e32 v57, 16, v35
	v_lshlrev_b32_e32 v56, 16, v34
	v_and_b32_e32 v35, 0xffff0000, v35
	v_and_b32_e32 v34, 0xffff0000, v34
	s_waitcnt vmcnt(3)
	v_lshlrev_b32_e32 v59, 16, v37
	v_lshlrev_b32_e32 v58, 16, v36
	s_waitcnt vmcnt(2)
	v_lshlrev_b32_e32 v61, 16, v39
	v_lshlrev_b32_e32 v60, 16, v38
	v_and_b32_e32 v63, 0xffff0000, v37
	v_and_b32_e32 v62, 0xffff0000, v36
	v_and_b32_e32 v37, 0xffff0000, v39
	v_and_b32_e32 v36, 0xffff0000, v38
	s_waitcnt vmcnt(0)
	v_lshlrev_b32_e32 v39, 16, v53
	v_lshlrev_b32_e32 v38, 16, v52
	v_and_b32_e32 v53, 0xffff0000, v53
	v_and_b32_e32 v52, 0xffff0000, v52
	v_cndmask_b32_e64 v66, v49, v66, s[0:1]
	v_lshlrev_b32_e32 v55, 16, v33
	v_lshlrev_b32_e32 v54, 16, v32
	v_and_b32_e32 v33, 0xffff0000, v33
	v_and_b32_e32 v32, 0xffff0000, v32
	v_lshlrev_b32_e32 v65, 16, v51
	v_lshlrev_b32_e32 v64, 16, v50
	v_and_b32_e32 v51, 0xffff0000, v51
	v_and_b32_e32 v50, 0xffff0000, v50
	v_pk_mul_f32 v[26:27], v[66:67], v[26:27] op_sel_hi:[0,1]
	v_pk_mul_f32 v[30:31], v[66:67], v[30:31] op_sel_hi:[0,1]
	v_pk_mul_f32 v[56:57], v[66:67], v[56:57] op_sel_hi:[0,1]
	v_pk_mul_f32 v[68:69], v[66:67], v[34:35] op_sel_hi:[0,1]
	v_pk_mul_f32 v[60:61], v[66:67], v[60:61] op_sel_hi:[0,1]
	v_pk_mul_f32 v[70:71], v[66:67], v[36:37] op_sel_hi:[0,1]
	v_pk_mul_f32 v[72:73], v[66:67], v[38:39] op_sel_hi:[0,1]
	v_pk_mul_f32 v[52:53], v[66:67], v[52:53] op_sel_hi:[0,1]
	v_pk_fma_f32 v[38:39], v[12:13], v[26:27], v[24:25]
	v_pk_fma_f32 v[36:37], v[10:11], v[30:31], v[28:29]
	v_pk_fma_f32 v[34:35], v[0:1], v[56:57], v[54:55]
	v_pk_fma_f32 v[32:33], v[22:23], v[68:69], v[32:33]
	v_pk_fma_f32 v[30:31], v[4:5], v[60:61], v[58:59]
	v_pk_fma_f32 v[28:29], v[2:3], v[70:71], v[62:63]
	v_pk_fma_f32 v[26:27], v[8:9], v[72:73], v[64:65]
	v_pk_fma_f32 v[24:25], v[6:7], v[52:53], v[50:51]
	s_cbranch_vccz .LBB0_1763
	s_add_i32 s38, s30, 0x8100
	s_cmp_gt_i32 s38, 0x80ff
	s_mov_b64 s[26:27], -1
	s_cbranch_scc1 .LBB0_1766
	s_andn2_b64 vcc, exec, s[26:27]
	s_cbranch_vccz .LBB0_1767

; __device__ __forceinline__ unsigned pk2(float lo, float hi) { return f2bf(lo) | (f2bf(hi) << 16); }
; __device__ __forceinline__ float wave_sum(float v) {
; #pragma unroll
;     for (int o = 1; o < 64; o <<= 1) v += __shfl_xor(v, o);
;     return v;
; }
; __device__ __forceinline__ void nr_pass(bf16* X, const bf16* Y, const float* SSQ, float* ssqX, const float* g, float* out  , int gw, int NGW, int lane) {
;     ...
;         if (out == nullptr) {
;             s2 = wave_sum(s2);
; #pragma unroll
;             for (int j = 0; j < 4; ++j) x8[64 * j] = (v2u){pk2(v[j].x, v[j].y), pk2(v[j].z, v[j].w)};
;             if (lane == 0) ssqX[r] = s2;
.LBB0_1763:
	s_cbranch_execz .LBB0_1756
	v_pk_mul_f32 v[50:51], v[36:37], v[36:37]
	v_pk_mul_f32 v[52:53], v[32:33], v[32:33]
	v_pk_fma_f32 v[50:51], v[38:39], v[38:39], v[50:51]
	v_pk_fma_f32 v[52:53], v[34:35], v[34:35], v[52:53]
	v_pk_mul_f32 v[54:55], v[28:29], v[28:29]
	v_pk_mul_f32 v[56:57], v[24:25], v[24:25]
	v_pk_fma_f32 v[54:55], v[30:31], v[30:31], v[54:55]
	v_add_f32_e32 v49, v52, v53
	v_add_f32_e32 v50, v50, v51
	v_pk_fma_f32 v[56:57], v[26:27], v[26:27], v[56:57]
	v_add_f32_e32 v49, v50, v49
	v_add_f32_e32 v50, v54, v55
	v_add_f32_e32 v49, v50, v49
	v_add_f32_e32 v50, v56, v57
	v_add_f32_e32 v49, v49, v50
	s_nop 1
	v_mov_b32_dpp v50, v49 quad_perm:[1,0,3,2] row_mask:0xf bank_mask:0xf
	v_and_b32_sdwa v59, v37, v48 dst_sel:DWORD dst_unused:UNUSED_PAD src0_sel:WORD_1 src1_sel:DWORD
	v_and_b32_sdwa v60, v36, v48 dst_sel:DWORD dst_unused:UNUSED_PAD src0_sel:WORD_1 src1_sel:DWORD
	v_lshl_add_u64 v[52:53], v[14:15], 0, s[20:21]
	v_lshl_add_u64 v[54:55], v[14:15], 0, s[22:23]
	s_waitcnt lgkmcnt(0)
	v_add_f32_e32 v49, v49, v50
	s_nop 1
	v_mov_b32_dpp v50, v49 quad_perm:[2,3,0,1] row_mask:0xf bank_mask:0xf
	v_add3_u32 v37, v37, v59, s36
	v_add3_u32 v36, v36, v60, s36
	v_and_b32_e32 v37, 0xffff0000, v37
	v_and_b32_e32 v36, 0xffff0000, v36
	s_waitcnt lgkmcnt(0)
	v_add_f32_e32 v49, v49, v50
	s_nop 1
	v_mov_b32_dpp v56, v49 row_half_mirror row_mask:0xf bank_mask:0xf
	v_lshl_add_u64 v[50:51], v[14:15], 0, s[10:11]
	s_waitcnt lgkmcnt(0)
	v_add_f32_e32 v49, v49, v56
	v_lshl_add_u64 v[56:57], v[14:15], 0, s[24:25]
	v_and_b32_sdwa v14, v39, v48 dst_sel:DWORD dst_unused:UNUSED_PAD src0_sel:WORD_1 src1_sel:DWORD
	v_and_b32_sdwa v15, v38, v48 dst_sel:DWORD dst_unused:UNUSED_PAD src0_sel:WORD_1 src1_sel:DWORD
	s_nop 1
	v_mov_b32_dpp v58, v49 row_mirror row_mask:0xf bank_mask:0xf
	v_add3_u32 v38, v38, v15, s36
	v_add3_u32 v39, v39, v14, s36
	v_or_b32_sdwa v37, v37, v39 dst_sel:DWORD dst_unused:UNUSED_PAD src0_sel:DWORD src1_sel:WORD_1
	v_or_b32_sdwa v36, v36, v38 dst_sel:DWORD dst_unused:UNUSED_PAD src0_sel:DWORD src1_sel:WORD_1
	global_store_dwordx2 v[50:51], v[36:37], off
	v_and_b32_sdwa v36, v35, v48 dst_sel:DWORD dst_unused:UNUSED_PAD src0_sel:WORD_1 src1_sel:DWORD
	v_and_b32_sdwa v37, v34, v48 dst_sel:DWORD dst_unused:UNUSED_PAD src0_sel:WORD_1 src1_sel:DWORD
	v_add3_u32 v34, v34, v37, s36
	v_add3_u32 v35, v35, v36, s36
	v_and_b32_sdwa v36, v33, v48 dst_sel:DWORD dst_unused:UNUSED_PAD src0_sel:WORD_1 src1_sel:DWORD
	v_and_b32_sdwa v37, v32, v48 dst_sel:DWORD dst_unused:UNUSED_PAD src0_sel:WORD_1 src1_sel:DWORD
	v_add3_u32 v33, v33, v36, s36
	v_add3_u32 v32, v32, v37, s36
	s_waitcnt lgkmcnt(0)
	v_add_f32_e32 v49, v49, v58
	v_and_b32_e32 v33, 0xffff0000, v33
	v_and_b32_e32 v32, 0xffff0000, v32
	v_mov_b32_e32 v58, v49
	s_nop 1
	v_permlane16_swap_b32_e32 v58, v49
	v_or_b32_sdwa v33, v33, v35 dst_sel:DWORD dst_unused:UNUSED_PAD src0_sel:DWORD src1_sel:WORD_1
	v_or_b32_sdwa v32, v32, v34 dst_sel:DWORD dst_unused:UNUSED_PAD src0_sel:DWORD src1_sel:WORD_1
	global_store_dwordx2 v[52:53], v[32:33], off
	v_and_b32_sdwa v32, v31, v48 dst_sel:DWORD dst_unused:UNUSED_PAD src0_sel:WORD_1 src1_sel:DWORD
	v_and_b32_sdwa v33, v30, v48 dst_sel:DWORD dst_unused:UNUSED_PAD src0_sel:WORD_1 src1_sel:DWORD
	v_add3_u32 v30, v30, v33, s36
	v_add3_u32 v31, v31, v32, s36
	v_and_b32_sdwa v32, v29, v48 dst_sel:DWORD dst_unused:UNUSED_PAD src0_sel:WORD_1 src1_sel:DWORD
	v_and_b32_sdwa v33, v28, v48 dst_sel:DWORD dst_unused:UNUSED_PAD src0_sel:WORD_1 src1_sel:DWORD
	v_add3_u32 v29, v29, v32, s36
	v_add3_u32 v28, v28, v33, s36
	v_and_b32_e32 v29, 0xffff0000, v29
	v_and_b32_e32 v28, 0xffff0000, v28
	s_waitcnt lgkmcnt(0)
	v_add_f32_e32 v14, v49, v58
	v_or_b32_sdwa v29, v29, v31 dst_sel:DWORD dst_unused:UNUSED_PAD src0_sel:DWORD src1_sel:WORD_1
	v_or_b32_sdwa v28, v28, v30 dst_sel:DWORD dst_unused:UNUSED_PAD src0_sel:DWORD src1_sel:WORD_1
	v_mov_b32_e32 v15, v14
	s_nop 1
	v_permlane32_swap_b32_e32 v15, v14
	global_store_dwordx2 v[54:55], v[28:29], off
	v_and_b32_sdwa v28, v27, v48 dst_sel:DWORD dst_unused:UNUSED_PAD src0_sel:WORD_1 src1_sel:DWORD
	v_and_b32_sdwa v29, v26, v48 dst_sel:DWORD dst_unused:UNUSED_PAD src0_sel:WORD_1 src1_sel:DWORD
	v_add3_u32 v26, v26, v29, s36
	v_add3_u32 v27, v27, v28, s36
	v_and_b32_sdwa v28, v25, v48 dst_sel:DWORD dst_unused:UNUSED_PAD src0_sel:WORD_1 src1_sel:DWORD
	v_and_b32_sdwa v29, v24, v48 dst_sel:DWORD dst_unused:UNUSED_PAD src0_sel:WORD_1 src1_sel:DWORD
	v_add3_u32 v25, v25, v28, s36
	v_add3_u32 v24, v24, v29, s36
	v_and_b32_e32 v25, 0xffff0000, v25
	v_and_b32_e32 v24, 0xffff0000, v24
	v_or_b32_sdwa v25, v25, v27 dst_sel:DWORD dst_unused:UNUSED_PAD src0_sel:DWORD src1_sel:WORD_1
	v_or_b32_sdwa v24, v24, v26 dst_sel:DWORD dst_unused:UNUSED_PAD src0_sel:DWORD src1_sel:WORD_1
	global_store_dwordx2 v[56:57], v[24:25], off
	s_and_saveexec_b64 s[0:1], s[2:3]
	s_cbranch_execz .LBB0_1755
	s_add_u32 s26, s92, s31
	s_waitcnt lgkmcnt(0)
	v_add_f32_e32 v14, v14, v15
	s_addc_u32 s27, s93, s33
	global_store_dword v47, v14, s[26:27]
	s_branch .LBB0_1755
